# diff fast loop: P0 and P2 bf16 conversions and their row-sum MFMAs moved into the gaps after PV MFMAs 13 and 15 (shorter VALU-only tail before the barrier)
# speedup vs baseline: 1.0073x; 1.0073x over previous
.Lf_459:
	v_mov_b32_e32 v180, v128
	v_mov_b32_e32 v181, v129
	v_mov_b32_e32 v182, v130
	v_mov_b32_e32 v183, v131
	v_mfma_f32_32x32x16_bf16 v[64:79], v[176:179], v[140:143], v[64:79]
	ds_read_b64_tr_b16 v[128:129], v0 offset:24576
	ds_read_b64_tr_b16 v[130:131], v0 offset:25088
	v_exp_f32_e32 v14, v112
	v_mfma_f32_32x32x16_bf16 v[64:79], v[172:175], v[136:139], v[64:79]
	ds_read_b64_tr_b16 v[172:173], v0 offset:25600
	ds_read_b64_tr_b16 v[174:175], v0 offset:26112
	v_exp_f32_e32 v15, v96
	v_mfma_f32_32x32x16_bf16 v[64:79], v[168:171], v[132:135], v[64:79]
	ds_read_b64_tr_b16 v[168:169], v0 offset:26624
	ds_read_b64_tr_b16 v[170:171], v0 offset:27136
	v_exp_f32_e32 v96, v113
	v_mfma_f32_32x32x16_bf16 v[64:79], v[164:167], v[180:183], v[64:79]
	ds_read_b64_tr_b16 v[164:165], v0 offset:27648
	ds_read_b64_tr_b16 v[166:167], v0 offset:28160
	v_exp_f32_e32 v97, v97
	v_mfma_f32_32x32x16_bf16 v[48:63], v[160:163], v[140:143], v[48:63]
	ds_read_b64_tr_b16 v[160:161], v0 offset:28672
	ds_read_b64_tr_b16 v[162:163], v0 offset:29184
	v_exp_f32_e32 v112, v114
	v_mfma_f32_32x32x16_bf16 v[48:63], v[10:13], v[136:139], v[48:63]
	ds_read_b64_tr_b16 v[10:11], v0 offset:29696
	ds_read_b64_tr_b16 v[12:13], v0 offset:30208
	v_exp_f32_e32 v98, v98
	v_mfma_f32_32x32x16_bf16 v[48:63], v[6:9], v[132:135], v[48:63]
	ds_read_b64_tr_b16 v[6:7], v0 offset:30720
	ds_read_b64_tr_b16 v[8:9], v0 offset:31232
	v_exp_f32_e32 v113, v115
	v_mfma_f32_32x32x16_bf16 v[48:63], v[2:5], v[180:183], v[48:63]
	ds_read_b64_tr_b16 v[2:3], v0 offset:31744
	ds_read_b64_tr_b16 v[4:5], v0 offset:32256
	v_exp_f32_e32 v0, v99
	s_waitcnt lgkmcnt(14)
	v_mfma_f32_32x32x16_bf16 v[32:47], v[128:131], v[140:143], v[32:47]
	v_exp_f32_e32 v99, v116
	v_exp_f32_e32 v100, v100
	v_exp_f32_e32 v114, v117
	s_waitcnt lgkmcnt(12)
	v_mfma_f32_32x32x16_bf16 v[32:47], v[172:175], v[136:139], v[32:47]
	v_exp_f32_e32 v101, v101
	v_exp_f32_e32 v115, v118
	v_exp_f32_e32 v102, v102
	s_waitcnt lgkmcnt(10)
	v_mfma_f32_32x32x16_bf16 v[32:47], v[168:171], v[132:135], v[32:47]
	v_exp_f32_e32 v116, v119
	v_exp_f32_e32 v103, v103
	v_exp_f32_e32 v117, v120
	s_waitcnt lgkmcnt(8)
	v_mfma_f32_32x32x16_bf16 v[32:47], v[164:167], v[180:183], v[32:47]
	v_exp_f32_e32 v104, v104
	v_exp_f32_e32 v118, v121
	v_exp_f32_e32 v105, v105
	s_waitcnt lgkmcnt(6)
	v_mfma_f32_32x32x16_bf16 v[16:31], v[160:163], v[140:143], v[16:31]
	v_exp_f32_e32 v119, v122
	v_exp_f32_e32 v106, v106
	v_exp_f32_e32 v120, v123
	v_mfma_f32_4x4x4_16b_bf16 v[84:87], v[218:219], v[140:141], v[84:87]
	v_mfma_f32_4x4x4_16b_bf16 v[88:91], v[218:219], v[142:143], v[88:91]
	v_cvt_pk_bf16_f32 v140, v14, v96
	v_cvt_pk_bf16_f32 v141, v112, v113
	v_cvt_pk_bf16_f32 v142, v99, v114
	v_cvt_pk_bf16_f32 v143, v115, v116
	s_waitcnt lgkmcnt(4)
	v_mfma_f32_32x32x16_bf16 v[16:31], v[10:13], v[136:139], v[16:31]
	v_exp_f32_e32 v10, v107
	v_exp_f32_e32 v11, v124
	v_exp_f32_e32 v12, v108
	s_waitcnt lgkmcnt(2)
	v_mfma_f32_32x32x16_bf16 v[16:31], v[6:9], v[132:135], v[16:31]
	v_exp_f32_e32 v6, v125
	v_exp_f32_e32 v7, v109
	v_exp_f32_e32 v8, v126
	v_mfma_f32_4x4x4_16b_bf16 v[84:87], v[218:219], v[132:133], v[84:87]
	v_mfma_f32_4x4x4_16b_bf16 v[88:91], v[218:219], v[134:135], v[88:91]
	v_cvt_pk_bf16_f32 v132, v15, v97
	v_cvt_pk_bf16_f32 v133, v98, v0
	v_cvt_pk_bf16_f32 v134, v100, v101
	v_cvt_pk_bf16_f32 v135, v102, v103
	s_waitcnt lgkmcnt(0)
	v_mfma_f32_32x32x16_bf16 v[16:31], v[2:5], v[180:183], v[16:31]
	v_exp_f32_e32 v107, v110
	s_nop 0
	v_mfma_f32_4x4x4_16b_bf16 v[84:87], v[218:219], v[136:137], v[84:87]
	v_mfma_f32_4x4x4_16b_bf16 v[88:91], v[218:219], v[138:139], v[88:91]
	v_exp_f32_e32 v108, v127
	v_exp_f32_e32 v109, v111
	v_cvt_pk_bf16_f32 v136, v117, v118
	v_cvt_pk_bf16_f32 v137, v119, v120
	v_cvt_pk_bf16_f32 v138, v11, v6
	v_cvt_pk_bf16_f32 v139, v8, v108
	v_cvt_pk_bf16_f32 v128, v104, v105
	v_cvt_pk_bf16_f32 v129, v106, v10
	v_cvt_pk_bf16_f32 v130, v12, v7
	v_cvt_pk_bf16_f32 v131, v107, v109
	v_mfma_f32_4x4x4_16b_bf16 v[84:87], v[218:219], v[180:181], v[84:87]
	v_mfma_f32_4x4x4_16b_bf16 v[88:91], v[218:219], v[182:183], v[88:91]
	s_add_i32 s28, s28, 1
	s_add_i32 s13, s13, 1
	s_add_i32 s19, s19, 0x8000
	s_cmpk_eq_i32 s13, 0x45
	s_cbranch_scc1 .Lf_fold464
